# diff attention: ALiBi table reads issued ahead of the V/K fragment reads in each half-tile, counted lgkmcnt waits
# baseline (speedup 1.0000x reference)
; #define LAS __attribute__((address_space(3)))
; __device__ __forceinline__ float fast_exp2(float x) { return __builtin_amdgcn_exp2f(x); }
; template <int MODE, int NQ>
; __device__ __forceinline__ void attn_unit(LAS unsigned char* lds, const Params& P, int layer, int b, int h, int qb) {
;     ...
;             if (it + 2 < NT) { if (hf == 0) AT_GLOADK(AT_TILE(it + 2)); else AT_GLOADV(AT_TILE(it + 2)); }
;             f32x16 sc[NC];
; #pragma unroll
;             for (int cc = 0; cc < NC; ++cc) {
;                 sc[cc] = f32x16{};
; #pragma unroll
;                 for (int d0 = 0; d0 < ND0; ++d0) sc[cc] = __builtin_amdgcn_mfma_f32_32x32x16_bf16(kf[(cc % NMAP) * ND0 + d0], qf[cc][d0], sc[cc], 0, 0, 0);
;             }
;             __builtin_amdgcn_sched_barrier(0);
;             AT_VLOAD(cur, hf);
;             if (hf == 0) AT_KLOAD(cur, 1); else if (it + 1 < NT) AT_KLOAD(nxt, 0);
;             __builtin_amdgcn_sched_barrier(0);
;             bf16x8 pw[NC][2]; float rmrel[NC]; bool alive = false;
; #pragma unroll
;             for (int cc = 0; cc < NC; ++cc) {
;                 f32x16& s0 = sc[cc];
;                 float mn;
;                 if (MODE != 0) {
;                     const LAS f32x4* tp4 = (const LAS f32x4*)(tlane + (kt * 64 + hf * 32) * 4);
;                     float rm = -3e38f;
; #pragma unroll
;                     for (int g = 0; g < 4; ++g) { const f32x4 t4 = tp4[2 * g];
; #pragma unroll
;                         for (int i = 0; i < 4; ++i) { s0[4 * g + i] = s0[4 * g + i] * c + t4[i]; rm = fmaxf(rm, s0[4 * g + i]); } }
;                     rm = xmax(rm);
;                     mn = fmaxf(mrun[cc], rm);
;                     rmrel[cc] = rm;
;                 } else {
;                     float rm = -3e38f;
; #pragma unroll
;                     for (int r = 0; r < 16; ++r) rm = fmaxf(rm, s0[r]);
;                     rm = xmax(rm);
;                     mn = fmaxf(mrun[cc], rm * c);
;                 }
;                 if (__any(mn > mrun[cc] + AT_THR)) {
;                     const float al = fast_exp2(mrun[cc] - mn); lrun[cc] *= al;
; #pragma unroll
;                     for (int r = 0; r < 16; ++r) { o[cc][0][r] *= al; o[cc][1][r] *= al; }
;                     mrun[cc] = mn;
;                 }
.LBB0_410:
	s_mul_i32 s10, s9, 0x5000
	s_add_i32 s16, s10, 0
	s_add_i32 s10, s5, s8
	s_add_i32 s11, s10, 0xffffe000
	s_cmp_gt_u32 s7, 31
	v_add3_u32 v0, s16, v193, v192
	s_cselect_b32 s10, s11, s10
	v_add_u32_e32 v199, v0, v189
	v_add_u32_e32 v0, s10, v191
	s_add_i32 s10, s7, 2
	s_sub_i32 s11, s7, 30
	s_cmp_gt_u32 s10, 31
	s_cselect_b32 s10, s11, s10
	s_ashr_i32 s11, s10, 31
	s_lshl_b64 s[10:11], s[10:11], 6
	v_lshl_add_u64 v[2:3], v[182:183], 0, s[10:11]
	v_mov_b64_e32 v[4:5], s[0:1]
	v_mad_u64_u32 v[4:5], s[14:15], v2, s27, v[4:5]
	v_mad_i32_i24 v5, v3, s27, v5
	global_load_dwordx4 v[2:5], v[4:5], off
	v_lshl_add_u64 v[228:229], v[178:179], 0, s[10:11]
	v_mad_u64_u32 v[230:231], s[14:15], v228, s27, v[180:181]
	v_mad_i32_i24 v231, v229, s27, v231
	global_load_dwordx4 v[224:227], v[230:231], off
	s_waitcnt lgkmcnt(3)
	v_mfma_f32_32x32x16_bf16 v[96:111], v[140:143], v[124:127], 0
	s_waitcnt lgkmcnt(1)
	v_mfma_f32_32x32x16_bf16 v[80:95], v[132:135], v[120:123], 0
	v_mfma_f32_32x32x16_bf16 v[96:111], v[136:139], v[116:119], v[96:111]
	s_waitcnt lgkmcnt(0)
	v_mfma_f32_32x32x16_bf16 v[80:95], v[128:131], v[112:115], v[80:95]
	ds_read_b128 v[156:159], v0 offset:61440
	ds_read_b128 v[152:155], v0 offset:61472
	ds_read_b128 v[164:167], v0 offset:61504
	ds_read_b128 v[172:175], v0 offset:61536
	ds_read_b64_tr_b16 v[148:149], v199 offset:12288
	ds_read_b64_tr_b16 v[150:151], v199 offset:12800
	ds_read_b64_tr_b16 v[144:145], v199 offset:13312
	ds_read_b64_tr_b16 v[146:147], v199 offset:13824
	ds_read_b64_tr_b16 v[140:141], v199 offset:16384
	ds_read_b64_tr_b16 v[142:143], v199 offset:16896
	ds_read_b64_tr_b16 v[136:137], v199 offset:17408
	ds_read_b64_tr_b16 v[138:139], v199 offset:17920
	v_add3_u32 v6, s16, v195, v196
	ds_read_b128 v[132:135], v6 offset:512
	ds_read_b128 v[128:131], v6 offset:2560
	ds_read_b128 v[10:13], v6 offset:4608
	ds_read_b128 v[6:9], v6 offset:6656
	s_waitcnt lgkmcnt(15)
	v_pk_fma_f32 v[160:161], v[96:97], s[34:35], v[156:157] op_sel_hi:[1,0,1]
	v_pk_fma_f32 v[98:99], v[98:99], s[34:35], v[158:159] op_sel_hi:[1,0,1]
	v_max3_f32 v96, v160, s68, v161
	s_waitcnt lgkmcnt(14)
	v_pk_fma_f32 v[14:15], v[100:101], s[34:35], v[152:153] op_sel_hi:[1,0,1]
	v_max3_f32 v96, v96, v98, v99
	v_max3_f32 v100, v96, v14, v15
	v_pk_fma_f32 v[96:97], v[102:103], s[34:35], v[154:155] op_sel_hi:[1,0,1]
	s_waitcnt lgkmcnt(13)
	v_pk_fma_f32 v[104:105], v[104:105], s[34:35], v[164:165] op_sel_hi:[1,0,1]
	v_max3_f32 v100, v100, v96, v97
	v_max3_f32 v102, v100, v104, v105
	v_pk_fma_f32 v[100:101], v[106:107], s[34:35], v[166:167] op_sel_hi:[1,0,1]
	s_nop 0
	v_max3_f32 v106, v102, v100, v101
	s_waitcnt lgkmcnt(12)
	v_pk_fma_f32 v[102:103], v[108:109], s[34:35], v[172:173] op_sel_hi:[1,0,1]
	s_nop 0
	v_max3_f32 v108, v106, v102, v103
	v_pk_fma_f32 v[106:107], v[110:111], s[34:35], v[174:175] op_sel_hi:[1,0,1]
	s_nop 0
	v_max3_f32 v108, v108, v106, v107
	v_mov_b32_e32 v109, v108
	s_nop 1
	v_permlane32_swap_b32_e32 v108, v109
	v_max_f32_e32 v108, v108, v109
	v_max_f32_e32 v200, v198, v108
	v_add_f32_e32 v109, 0x41000000, v198
	s_waitcnt lgkmcnt(0)
	v_cmp_gt_f32_e32 vcc, v200, v109
	s_cbranch_vccz .LBB0_412
	v_sub_f32_e32 v109, v198, v200
	s_mov_b32 s61, 0
	v_exp_f32_e32 v110, v109
	s_nop 0
	v_mul_f32_e32 v188, v188, v110
	v_pk_mul_f32 v[78:79], v[78:79], v[110:111] op_sel_hi:[1,0]
	v_pk_mul_f32 v[76:77], v[76:77], v[110:111] op_sel_hi:[1,0]
	v_pk_mul_f32 v[74:75], v[74:75], v[110:111] op_sel_hi:[1,0]
	v_pk_mul_f32 v[72:73], v[72:73], v[110:111] op_sel_hi:[1,0]
	v_pk_mul_f32 v[70:71], v[70:71], v[110:111] op_sel_hi:[1,0]
	v_pk_mul_f32 v[68:69], v[68:69], v[110:111] op_sel_hi:[1,0]
	v_pk_mul_f32 v[66:67], v[66:67], v[110:111] op_sel_hi:[1,0]
	v_pk_mul_f32 v[64:65], v[64:65], v[110:111] op_sel_hi:[1,0]
	v_pk_mul_f32 v[30:31], v[30:31], v[110:111] op_sel_hi:[1,0]
	v_pk_mul_f32 v[28:29], v[28:29], v[110:111] op_sel_hi:[1,0]
	v_pk_mul_f32 v[26:27], v[26:27], v[110:111] op_sel_hi:[1,0]
	v_pk_mul_f32 v[24:25], v[24:25], v[110:111] op_sel_hi:[1,0]
	v_pk_mul_f32 v[22:23], v[22:23], v[110:111] op_sel_hi:[1,0]
	v_pk_mul_f32 v[20:21], v[20:21], v[110:111] op_sel_hi:[1,0]
	v_pk_mul_f32 v[18:19], v[18:19], v[110:111] op_sel_hi:[1,0]
	v_pk_mul_f32 v[16:17], v[16:17], v[110:111] op_sel_hi:[1,0]
	s_branch .LBB0_413

; #define LAS __attribute__((address_space(3)))
; __device__ __forceinline__ float fast_exp2(float x) { return __builtin_amdgcn_exp2f(x); }
; __device__ __forceinline__ float xmax(float a) { auto rr = __builtin_amdgcn_permlane32_swap(__float_as_uint(a), __float_as_uint(a), false, false); return fmaxf(__uint_as_float(rr[0]), __uint_as_float(rr[1])); }
; template <int MODE, int NQ>
; __device__ __forceinline__ void attn_unit(LAS unsigned char* lds, const Params& P, int layer, int b, int h, int qb) {
;     ...
;             for (int cc = 0; cc < NC; ++cc) {
;                 sc[cc] = f32x16{};
; #pragma unroll
;                 for (int d0 = 0; d0 < ND0; ++d0) sc[cc] = __builtin_amdgcn_mfma_f32_32x32x16_bf16(kf[(cc % NMAP) * ND0 + d0], qf[cc][d0], sc[cc], 0, 0, 0);
;             }
;             __builtin_amdgcn_sched_barrier(0);
;             AT_VLOAD(cur, hf);
;             if (hf == 0) AT_KLOAD(cur, 1); else if (it + 1 < NT) AT_KLOAD(nxt, 0);
;             __builtin_amdgcn_sched_barrier(0);
;             bf16x8 pw[NC][2]; float rmrel[NC]; bool alive = false;
; #pragma unroll
;             for (int cc = 0; cc < NC; ++cc) {
;                 f32x16& s0 = sc[cc];
;                 float mn;
;                 if (MODE != 0) {
;                     const LAS f32x4* tp4 = (const LAS f32x4*)(tlane + (kt * 64 + hf * 32) * 4);
;                     float rm = -3e38f;
; #pragma unroll
;                     for (int g = 0; g < 4; ++g) { const f32x4 t4 = tp4[2 * g];
; #pragma unroll
;                         for (int i = 0; i < 4; ++i) { s0[4 * g + i] = s0[4 * g + i] * c + t4[i]; rm = fmaxf(rm, s0[4 * g + i]); } }
;                     rm = xmax(rm);
;                     mn = fmaxf(mrun[cc], rm);
;                     rmrel[cc] = rm;
;                 } else {
;                     float rm = -3e38f;
; #pragma unroll
;                     for (int r = 0; r < 16; ++r) rm = fmaxf(rm, s0[r]);
;                     rm = xmax(rm);
;                     mn = fmaxf(mrun[cc], rm * c);
;                 }
;                 if (__any(mn > mrun[cc] + AT_THR)) {
;                     const float al = fast_exp2(mrun[cc] - mn); lrun[cc] *= al;
; #pragma unroll
;                     for (int r = 0; r < 16; ++r) { o[cc][0][r] *= al; o[cc][1][r] *= al; }
;                     mrun[cc] = mn;
;                 }
.LBB0_422:
	s_add_i32 s14, s9, 1
	s_cmp_lg_u32 s9, 2
	s_cselect_b32 s9, s14, 0
	s_mul_i32 s15, s9, 0x5000
	s_add_i32 s10, s15, 0x5000
	s_cmp_lg_u32 s9, 2
	s_cselect_b32 s14, s10, 0
	v_add_u32_e32 v202, s14, v194
	v_mfma_f32_32x32x16_bf16 v[96:111], v[132:135], v[124:127], 0
	v_mfma_f32_32x32x16_bf16 v[80:95], v[10:13], v[120:123], 0
	v_mfma_f32_32x32x16_bf16 v[96:111], v[128:131], v[116:119], v[96:111]
	v_mfma_f32_32x32x16_bf16 v[80:95], v[6:9], v[112:115], v[80:95]
	ds_read_b128 v[156:159], v0 offset:61568
	ds_read_b128 v[152:155], v0 offset:61600
	ds_read_b128 v[164:167], v0 offset:61632
	ds_read_b128 v[172:175], v0 offset:61664
	ds_read_b64_tr_b16 v[148:149], v199 offset:14336
	ds_read_b64_tr_b16 v[150:151], v199 offset:14848
	ds_read_b64_tr_b16 v[144:145], v199 offset:15360
	ds_read_b64_tr_b16 v[146:147], v199 offset:15872
	ds_read_b64_tr_b16 v[10:11], v199 offset:18432
	ds_read_b64_tr_b16 v[12:13], v199 offset:18944
	ds_read_b64_tr_b16 v[6:7], v199 offset:19456
	ds_read_b64_tr_b16 v[8:9], v199 offset:19968
	v_add_u32_e32 v14, s15, v190
	ds_read_b128 v[140:143], v14
	ds_read_b128 v[136:139], v14 offset:2048
	ds_read_b128 v[132:135], v14 offset:4096
	ds_read_b128 v[128:131], v14 offset:6144
	s_waitcnt lgkmcnt(15)
	v_pk_fma_f32 v[160:161], v[96:97], s[34:35], v[156:157] op_sel_hi:[1,0,1]
	v_pk_fma_f32 v[98:99], v[98:99], s[34:35], v[158:159] op_sel_hi:[1,0,1]
	v_max3_f32 v96, v160, s68, v161
	s_waitcnt lgkmcnt(14)
	v_pk_fma_f32 v[14:15], v[100:101], s[34:35], v[152:153] op_sel_hi:[1,0,1]
	v_max3_f32 v96, v96, v98, v99
	v_max3_f32 v100, v96, v14, v15
	v_pk_fma_f32 v[96:97], v[102:103], s[34:35], v[154:155] op_sel_hi:[1,0,1]
	s_waitcnt lgkmcnt(13)
	v_pk_fma_f32 v[104:105], v[104:105], s[34:35], v[164:165] op_sel_hi:[1,0,1]
	v_max3_f32 v100, v100, v96, v97
	v_max3_f32 v0, v100, v104, v105
	v_pk_fma_f32 v[100:101], v[106:107], s[34:35], v[166:167] op_sel_hi:[1,0,1]
	s_waitcnt lgkmcnt(12)
	v_pk_fma_f32 v[102:103], v[108:109], s[34:35], v[172:173] op_sel_hi:[1,0,1]
	v_max3_f32 v0, v0, v100, v101
	v_max3_f32 v0, v0, v102, v103
	v_pk_fma_f32 v[106:107], v[110:111], s[34:35], v[174:175] op_sel_hi:[1,0,1]
	s_nop 0
	v_max3_f32 v0, v0, v106, v107
	v_mov_b32_e32 v108, v0
	s_nop 1
	v_permlane32_swap_b32_e32 v0, v108
	v_max_f32_e32 v0, v0, v108
	v_max_f32_e32 v198, v200, v0
	v_add_f32_e32 v108, 0x41000000, v200
	s_waitcnt lgkmcnt(0)
	v_cmp_gt_f32_e32 vcc, v198, v108
	s_cbranch_vccz .LBB0_424
	v_sub_f32_e32 v108, v200, v198
	s_mov_b32 s61, 0
	v_exp_f32_e32 v108, v108
	s_nop 0
	v_mul_f32_e32 v188, v188, v108
	v_pk_mul_f32 v[78:79], v[78:79], v[108:109] op_sel_hi:[1,0]
	v_pk_mul_f32 v[76:77], v[76:77], v[108:109] op_sel_hi:[1,0]
	v_pk_mul_f32 v[74:75], v[74:75], v[108:109] op_sel_hi:[1,0]
	v_pk_mul_f32 v[72:73], v[72:73], v[108:109] op_sel_hi:[1,0]
	v_pk_mul_f32 v[70:71], v[70:71], v[108:109] op_sel_hi:[1,0]
	v_pk_mul_f32 v[68:69], v[68:69], v[108:109] op_sel_hi:[1,0]
	v_pk_mul_f32 v[66:67], v[66:67], v[108:109] op_sel_hi:[1,0]
	v_pk_mul_f32 v[64:65], v[64:65], v[108:109] op_sel_hi:[1,0]
	v_pk_mul_f32 v[30:31], v[30:31], v[108:109] op_sel_hi:[1,0]
	v_pk_mul_f32 v[28:29], v[28:29], v[108:109] op_sel_hi:[1,0]
	v_pk_mul_f32 v[26:27], v[26:27], v[108:109] op_sel_hi:[1,0]
	v_pk_mul_f32 v[24:25], v[24:25], v[108:109] op_sel_hi:[1,0]
	v_pk_mul_f32 v[22:23], v[22:23], v[108:109] op_sel_hi:[1,0]
	v_pk_mul_f32 v[20:21], v[20:21], v[108:109] op_sel_hi:[1,0]
	v_pk_mul_f32 v[18:19], v[18:19], v[108:109] op_sel_hi:[1,0]
	v_pk_mul_f32 v[16:17], v[16:17], v[108:109] op_sel_hi:[1,0]
	s_branch .LBB0_425
